# split PB->PC grid barrier: arrive (flush + counter) after tile 7 of 9 (tile 8 = GF gate columns, not read until PE), wait (poll + invalidate) at the seam
# speedup vs baseline: 1.0003x; 1.0003x over previous
.LBB0_469:
	s_cmpk_lg_i32 s13, 0x100
	s_cbranch_scc1 .Lsb1_noarr
	s_cmp_lg_u32 s85, 8
	s_cbranch_scc1 .Lsb1_noarr
	s_waitcnt vmcnt(0)
	s_barrier
	v_readfirstlane_b32 s2, v220
	s_lshr_b32 s2, s2, 6
	s_cmp_lg_u32 s2, 0
	s_cbranch_scc1 .Lsb1_noarr
	v_readlane_b32 s4, v255, 2
	v_readlane_b32 s5, v255, 3
	s_add_u32 s4, s4, 0x24000
	s_addc_u32 s5, s5, 0
	buffer_wbl2 sc1
	s_waitcnt vmcnt(0)
	v_mov_b32_e32 v0, 0
	v_mov_b32_e32 v1, 1
	s_mov_b64 s[6:7], exec
	s_mov_b64 exec, 1
	global_atomic_add v0, v1, s[4:5]
	s_waitcnt vmcnt(0)
	s_mov_b64 exec, s[6:7]

.LBB0_472:
	s_cmpk_lg_i32 s13, 0x100
	s_cbranch_scc1 .Lsb1_orig
	v_readfirstlane_b32 s2, v220
	s_lshr_b32 s2, s2, 6
	s_cmp_lg_u32 s2, 0
	s_cbranch_scc1 .Lsb1_wait
	v_readlane_b32 s4, v255, 2
	v_readlane_b32 s5, v255, 3
	s_add_u32 s4, s4, 0x24000
	s_addc_u32 s5, s5, 0
	s_add_u32 s6, s92, 1
	s_lshl_b32 s6, s6, 8
	v_mov_b32_e32 v0, 0
	s_mov_b64 s[10:11], exec
	s_mov_b64 exec, 1
	s_mov_b32 s3, 0
.Lsb1_poll:
	global_load_dword v1, v0, s[4:5] sc1
	s_waitcnt vmcnt(0)
	v_readfirstlane_b32 s2, v1
	s_cmp_ge_u32 s2, s6
	s_cbranch_scc1 .Lsb1_done
	s_add_u32 s3, s3, 1
	s_cmp_gt_u32 s3, 0x10000
	s_cbranch_scc1 .Lsb1_done
	s_sleep 1
	s_branch .Lsb1_poll
.Lsb1_done:
	buffer_inv sc1
	s_waitcnt vmcnt(0)
	s_mov_b64 exec, s[10:11]
.Lsb1_wait:
	s_barrier
	s_branch .LBB0_520
.Lsb1_orig:
	s_waitcnt vmcnt(0)
	v_mov_b32_e32 v0, v220
	s_waitcnt vmcnt(0)
	s_barrier
	s_nop 0
	v_cmp_eq_u32_e32 vcc, 0, v0
	s_and_saveexec_b64 s[2:3], vcc
	s_cbranch_execz .LBB0_519
	v_readlane_b32 s4, v255, 6
	s_waitcnt vmcnt(0) expcnt(0) lgkmcnt(0)
	s_nop 0
	v_mov_b32_e32 v0, s4
	ds_read_b32 v2, v0
	ds_read_b32 v0, v0 offset:4
	s_waitcnt lgkmcnt(1)
	v_cmp_ne_u32_e32 vcc, 0, v2
	s_cbranch_vccnz .LBB0_487
	v_readlane_b32 s6, v255, 0
	v_readlane_b32 s7, v255, 1
	s_load_dwordx2 s[4:5], s[6:7], 0x4
	s_mov_b32 s15, 0
	s_waitcnt lgkmcnt(0)
	s_mul_i32 s11, s4, s13
	s_mul_i32 s11, s11, s5
	s_branch .LBB0_476
